# same as the permlane-swap version, with the unit index and completion threshold taken from the launched grid size instead of a constant 256
# baseline (speedup 1.0000x reference)
;     __device__ bool next(int i, Unit& u) const {
;         const long L = (long)i * G + c;
;         if (L >= nwg + n1M * n1N) return false;
;         if (L >= nwg) { const int r = (int)L - nwg; u.pm = r / n1N; u.pn = r % n1N; u.sel = 1; return true; }
;         int wgid = (int)L; { const int q = nwg / NXCD, r = nwg % NXCD, xcd = wgid % NXCD, off = wgid / NXCD; wgid = (xcd < r ? xcd * (q + 1) : r * (q + 1) + (xcd - r) * q) + off; }
;         const int nig = wgm * nN, gid = wgid / nig, fm = gid * wgm, gsz = (nM - fm) < wgm ? (nM - fm) : wgm;
;         u.pm = fm + ((wgid % nig) % gsz); u.pn = (wgid % nig) / gsz; u.sel = 0; return true;
.LBB0_255:
	s_add_i32 s20, s20, 1
	v_readlane_b32 s28, v254, 2
	s_mul_i32 s28, s28, s20
	s_add_i32 s28, s28, s95
	s_cmp_lg_u32 s98, 0
	s_cbranch_scc1 .Lord2_B
	s_cmpk_lt_u32 s28, 0x2f7
	s_cselect_b64 s[4:5], -1, 0
	s_and_b32 s23, s28, 7
	s_lshr_b32 s24, s28, 3
	s_mul_i32 s23, s23, 0x5f
	s_add_i32 s23, s23, s24
	s_mul_hi_u32 s24, s23, 0x2c8590c
	s_mul_i32 s25, s24, 0x5c
	s_sub_i32 s25, s23, s25
	s_lshl_b32 s26, s24, 2
	s_and_b32 s23, s25, 3
	s_add_i32 s26, s26, s23
	s_lshr_b32 s22, s25, 2
	s_cmp_eq_u32 s24, 8
	s_cselect_b32 s26, 32, s26
	s_cselect_b32 s22, s25, s22
	s_cmp_eq_u32 s22, 22
	s_cselect_b32 s22, 26, s22
	s_mov_b32 s16, 0
	s_branch .Lord2_done

; #define GROUP_LOOP(qi, total, ...) for (int gi_ = 0;; ++gi_) { if (threadIdx.x == 0) ctlw[22 + (gi_ & 1)] = __hip_atomic_fetch_add(qbase + 64 * (qi), 1u, __ATOMIC_RELAXED, __HIP_MEMORY_SCOPE_AGENT); \
;         group_bar(gb, lane); const int u = (int)ctlw[22 + (gi_ & 1)]; if (u >= (total)) break; __VA_ARGS__ }
; template <int MASK> __device__ __forceinline__ void phase3(const Params& p, LAS unsigned char* lds, volatile LAS unsigned* ctlw, int qset) {
;     ...
;             GROUP_LOOP(3, U_MEMP + U_MEMS, {
;                 if (u < U_MEMP) { const int hm = u & 3, qb = (u >> 2) & 15, b = u >> 6; const size_t r0 = (size_t)(b * SEQ + qb * 128);
;                     attn_unit<1>(lds, gb, PROJ + r0 * NPAD + PC_MQ + hm * 128, NPAD, (const bf16_t*)(p.ws + WS_MKN) + (size_t)(b * MEMT) * 512 + hm * 128, (const bf16_t*)(p.ws + WS_MVB) + (size_t)(b * MEMT) * 512 + hm * 128, 512,
.Lmem_poll:
	global_load_dword v1, v2, s[90:91] offset:2048 sc1
	s_waitcnt vmcnt(0)
	v_readfirstlane_b32 s4, v1
	v_readlane_b32 s6, v254, 2
	s_cmp_ge_u32 s4, s6
	s_cbranch_scc1 .Lmem_poll_done
	s_add_i32 s5, s5, -1
	s_cmp_eq_u32 s5, 0
	s_cbranch_scc1 .Lmem_poll_done
	s_sleep 8
	s_branch .Lmem_poll
